# P2: IUt/DUt rows requested a full item ahead (end of E1 of the previous item), one loop-invariant shift_mu quad kept in registers for the whole phase: item-top load burst 18 -> 15 loads
# baseline (speedup 1.0000x reference)
; __device__ void rwkv_prep_item(const Params& p, char* lds_, int item, PrepRaw& raw, int next_item) {
;     ...
;   const int tid = threadIdx.x, lane = tid & 63, wave = tid >> 6;
;   const int b = item >> 9, hd = (item >> 6) & 7, c = item & 63;
;   constexpr int RB = 64 * LD * 2;
;   u16* At = (u16*)(lds + 0 * RB);  u16* Bt = (u16*)(lds + 1 * RB);  u16* Kt = (u16*)(lds + 2 * RB);  u16* Rt = (u16*)(lds + 3 * RB);
;   u16* AT = (u16*)(lds + 4 * RB);  u16* BT = (u16*)(lds + 5 * RB);  u16* KT = (u16*)(lds + 6 * RB);  u16* VT = (u16*)(lds + 7 * RB);
;   u16* LAK = (u16*)(lds + 8 * RB); u16* MRB = (u16*)(lds + 9 * RB); u16* MRK = (u16*)(lds + 10 * RB); u16* TB = (u16*)(lds + 11 * RB);
;   float* Tf = (float*)(lds + 12 * RB);
;   float* gC = (float*)(lds + 12 * RB + 64 * 68 * 4);
;   float* Za = (float*)(lds + 12 * RB + 64 * 68 * 4 + 256);
;   u16* X1T = At; u16* WT = Bt; u16* U0T = Kt;
;   u16* TW = LAK; u16* AD = MRB; u16* DUs = MRK; u16* IUs = TB;
;   float* Zw = Tf; float* G = Tf;
;   const int t = tid >> 3, cg8 = (tid & 7) * 8;
;   const int pos = c * 64 + t;
;   const size_t tokrow = (size_t)b * SEQ + pos;
;   const u16* prow = p.PB + tokrow * PBW;
;   const bool hasprev = pos > 0;
;   float rr[8], kk_[8], vv[8];
;   f32x4 pdb[2], pib[2], pkk[2], pka[2], prk[2];
;     ...
;       const int j0 = (jt0 + jj) * 16 + 4 * mg;
;       f32x4 o; float x1[4], x2[4], x3[4];
; #pragma unroll
;       for (int e = 0; e < 4; ++e) {
;         const int j = j0 + e;
;         o[e] = (j < mi) ? lab[jj][e] : 0.f;
;         x1[e] = (j < mi) ? lak[jj][e] : 0.f;
;         x2[e] = (j <= mi) ? mrb[jj][e] : 0.f;
;         x3[e] = (j <= mi) ? mrk[jj][e] : 0.f;
;       }
.LBB0_273:
.LBB0_274:
	v_bfe_u32 v115, v223, 4, 2
	s_andn2_b64 vcc, exec, s[4:5]
	v_lshrrev_b32_e32 v158, 6, v223
	v_and_b32_e32 v174, 15, v223
	v_lshrrev_b32_e32 v175, 1, v223
	v_lshlrev_b32_e32 v114, 2, v115
	s_cbranch_vccnz .LBB0_330
	v_lshlrev_b32_e32 v28, 5, v158
	v_and_or_b32 v30, v28, 32, v174
	v_and_b32_e32 v29, 24, v175
	v_mul_u32_u24_e32 v24, 0x48, v30
	s_add_i32 s5, 0, 0x18d00
	v_and_b32_e32 v26, 0x70, v240
	v_lshlrev_b32_e32 v35, 1, v24
	v_or_b32_e32 v36, 32, v29
	v_or_b32_e32 v27, v26, v174
	v_lshlrev_b32_e32 v31, 1, v29
	v_lshlrev_b32_e32 v37, 1, v36
	v_add_u32_e32 v24, s5, v35
	v_add_u32_e32 v167, v24, v31
	v_add_u32_e32 v168, v24, v37
	v_mul_u32_u24_e32 v24, 0x44, v27
	v_bfe_u32 v25, v223, 6, 1
	v_lshlrev_b32_e32 v24, 2, v24
	s_add_i32 s15, 0, 0x1b100
	s_add_i32 s74, 0, 0x1f600
	v_add_u32_e32 v39, s15, v24
	v_add_u32_e32 v40, s74, v24
	v_lshlrev_b32_e32 v41, 7, v25
	v_and_b32_e32 v24, 48, v223
	v_and_b32_e32 v116, 56, v219
	v_add3_u32 v170, v39, v24, v41
	v_mul_u32_u24_e32 v39, 0x44, v240
	v_add_lshl_u32 v39, v39, v116, 2
	v_add_u32_e32 v172, s15, v39
	v_add_u32_e32 v173, s74, v39
	v_add_u32_e32 v39, 16, v39
	v_add_u32_e32 v176, s15, v39
	v_add_u32_e32 v177, s74, v39
	v_mbcnt_hi_u32_b32 v39, -1, v241
	v_add3_u32 v171, v40, v24, v41
	v_and_b32_e32 v41, 64, v39
	v_xor_b32_e32 v40, 1, v39
	v_add_u32_e32 v41, 64, v41
	v_cmp_lt_i32_e32 vcc, v40, v41
	v_mul_u32_u24_e32 v22, 0x48, v240
	v_mov_b32_e32 v242, v241
	v_cndmask_b32_e32 v40, v39, v40, vcc
	v_lshlrev_b32_e32 v178, 2, v40
	v_xor_b32_e32 v40, 2, v39
	v_cmp_lt_i32_e32 vcc, v40, v41
	s_add_i32 s14, 0, 0x12100
	v_lshlrev_b32_e32 v23, 1, v22
	v_cndmask_b32_e32 v40, v39, v40, vcc
	v_lshlrev_b32_e32 v179, 2, v40
	v_xor_b32_e32 v40, 4, v39
	v_cmp_lt_i32_e32 vcc, v40, v41
	v_lshlrev_b32_e32 v22, 1, v116
	s_add_i32 s4, 0, 0x14500
	v_cndmask_b32_e32 v39, v39, v40, vcc
	v_cmp_eq_u32_e32 vcc, 0, v174
	s_add_i32 s10, 0, 0x16900
	v_mul_u32_u24_e32 v47, 0x110, v24
	v_cndmask_b32_e64 v190, 0, 1.0, vcc
	v_cmp_eq_u32_e32 vcc, 1, v174
	v_lshlrev_b32_e32 v48, 2, v24
	v_add3_u32 v117, s14, v23, v22
	v_cndmask_b32_e64 v191, 0, 1.0, vcc
	v_cmp_eq_u32_e32 vcc, 2, v174
	v_cndmask_b32_e64 v253, 0, 1.0, vcc
	v_cmp_eq_u32_e32 vcc, 3, v174
	v_mul_u32_u24_e32 v32, 0x48, v27
	v_cndmask_b32_e64 v254, 0, 1.0, vcc
	v_cmp_eq_u32_e32 vcc, 4, v174
	v_add3_u32 v184, 0, v23, v22
	v_bitop3_b32 v23, v219, v240, 56 bitop3:0x6c
	v_cndmask_b32_e64 v255, 0, 1.0, vcc
	v_cmp_eq_u32_e32 vcc, 5, v174
	v_add3_u32 v189, s15, v47, v48
	v_lshlrev_b32_e32 v47, 2, v174
	v_cndmask_b32_e64 v241, 0, 1.0, vcc
	v_cmp_eq_u32_e32 vcc, 6, v174
	v_or_b32_e32 v48, 16, v28
	v_lshlrev_b32_e32 v120, 6, v25
	v_cndmask_b32_e64 v196, 0, 1.0, vcc
	v_cmp_eq_u32_e32 vcc, 7, v174
	v_lshlrev_b32_e32 v32, 1, v32
	s_movk_i32 s16, 0x110
	v_cndmask_b32_e64 v197, 0, 1.0, vcc
	v_cmp_eq_u32_e32 vcc, 8, v174
	v_mul_u32_u24_e32 v43, 0x90, v116
	v_lshlrev_b32_e32 v23, 1, v23
	v_cndmask_b32_e64 v198, 0, 1.0, vcc
	v_cmp_eq_u32_e32 vcc, 9, v174
	v_or_b32_e32 v49, v48, v174
	v_add3_u32 v211, s15, v120, v47
	v_or_b32_e32 v26, v114, v26
	v_add3_u32 v185, 0, v43, v23
	v_add_u32_e32 v23, 0, v32
	v_cndmask_b32_e64 v199, 0, 1.0, vcc
	v_cmp_eq_u32_e32 vcc, 10, v174
	v_mul_u32_u24_e32 v49, 0x110, v49
	v_lshl_add_u32 v50, v158, 7, s15
	v_or_b32_e32 v28, v28, v115
	v_mul_u32_u24_e32 v52, 0x84, v26
	v_mad_u32_u24 v212, v26, s16, v211
	v_bitop3_b32 v26, v27, v29, 56 bitop3:0x6c
	v_cndmask_b32_e64 v200, 0, 1.0, vcc
	v_cmp_eq_u32_e32 vcc, 11, v174
	v_add3_u32 v207, v50, v49, v114
	v_add_u32_e32 v49, v50, v47
	v_mul_u32_u24_e32 v50, 0x110, v28
	v_mul_u32_u24_e32 v28, 0x440, v158
	v_lshl_add_u32 v213, v26, 1, v23
	v_add_u32_e32 v26, s14, v35
	v_lshlrev_b32_e32 v180, 2, v39
	v_mul_u32_u24_e32 v39, 0x110, v240
	v_lshlrev_b32_e32 v40, 2, v116
	v_add_u32_e32 v43, 0, v35
	v_cndmask_b32_e64 v201, 0, 1.0, vcc
	v_cmp_eq_u32_e32 vcc, 12, v174
	v_add3_u32 v208, s74, v28, v47
	v_or_b32_e32 v28, v48, v114
	v_add_u32_e32 v214, v26, v31
	v_add_u32_e32 v216, v26, v37
	v_bitop3_b32 v26, v30, v29, 40 bitop3:0x6c
	v_add3_u32 v181, s15, v39, v40
	v_lshlrev_b32_e32 v39, 2, v222
	v_cndmask_b32_e64 v202, 0, 1.0, vcc
	v_cmp_eq_u32_e32 vcc, 13, v174
	v_mul_u32_u24_e32 v48, 0x110, v28
	v_bitop3_b32 v28, v27, v36, 56 bitop3:0x6c
	v_lshl_add_u32 v222, v26, 1, v43
	v_or_b32_e32 v26, 16, v30
	v_cndmask_b32_e64 v203, 0, 1.0, vcc
	v_cmp_eq_u32_e32 vcc, 14, v174
	v_lshl_add_u32 v215, v28, 1, v23
	v_mul_u32_u24_e32 v28, 0x48, v26
	s_add_i32 s44, 0, 0x1f500
	v_lshl_or_b32 v46, v25, 1, 1
	v_cndmask_b32_e64 v204, 0, 1.0, vcc
	v_cmp_eq_u32_e32 vcc, 15, v174
	v_lshl_add_u32 v28, v28, 1, 0
	v_bitop3_b32 v29, v26, v29, 56 bitop3:0x6c
	v_bitop3_b32 v26, v26, v36, 56 bitop3:0x6c
	v_lshl_or_b32 v25, v25, 5, v114
	s_cmp_lg_u32 0, -1
	v_cndmask_b32_e64 v205, 0, 1.0, vcc
	v_lshl_add_u32 v224, v29, 1, v28
	v_lshl_add_u32 v226, v26, 1, v28
	v_or_b32_e32 v28, 1, v25
	v_cmp_eq_u32_e32 vcc, v25, v27
	v_add_u32_e32 v41, s15, v39
	s_cselect_b64 s[76:77], -1, 0
	v_mov_b32_e32 v44, s15
	s_add_i32 s15, 0, 0x1fe80
	v_bitop3_b32 v29, v30, v36, 40 bitop3:0x6c
	v_cmp_lt_u32_e64 s[18:19], v28, v27
	v_cndmask_b32_e64 v122, 0, 1.0, vcc
	v_cmp_eq_u32_e32 vcc, v28, v27
	v_or_b32_e32 v28, 3, v25
	v_add_u32_e32 v33, s14, v32
	v_mad_u32_u24 v44, v27, s16, v44
	v_add_u32_e32 v206, v189, v47
	v_add3_u32 v47, s15, v120, v47
	v_add3_u32 v217, s14, v37, v35
	v_lshl_add_u32 v225, v29, 1, v43
	v_cmp_lt_u32_e64 s[14:15], v25, v27
	v_cmp_gt_u32_e64 s[16:17], v25, v27
	v_lshlrev_b32_e32 v29, 2, v25
	v_lshlrev_b32_e32 v26, 1, v25
	v_cndmask_b32_e64 v123, 0, 1.0, vcc
	v_or_b32_e32 v25, 2, v25
	v_cmp_eq_u32_e32 vcc, v28, v27
	s_load_dwordx2 s[78:79], s[0:1], 0xb8
	s_load_dwordx4 s[60:63], s[0:1], 0x18
	s_load_dwordx2 s[80:81], s[0:1], 0x30
	s_load_dwordx4 s[64:67], s[0:1], 0x40
	s_load_dwordx2 s[82:83], s[0:1], 0x50
	s_load_dwordx2 s[84:85], s[0:1], 0xf0
	v_cmp_lt_u32_e64 s[20:21], v25, v27
	v_cmp_gt_u32_e64 s[22:23], v25, v27
	v_cndmask_b32_e64 v125, 0, 1.0, vcc
	v_cmp_eq_u32_e32 vcc, v25, v27
	v_lshl_or_b32 v25, v46, 4, v114
	s_load_dwordx8 s[52:59], s[0:1], 0xd0
	v_mov_b32_e32 v119, 0
	v_lshlrev_b32_e32 v30, 2, v25
	v_or_b32_e32 v118, 0x1800, v40
	v_add_u32_e32 v183, s44, v40
	v_lshl_add_u32 v228, v27, 2, s44
	v_add_u32_e32 v229, v44, v29
	v_cmp_lt_u32_e64 s[24:25], v28, v27
	v_cmp_gt_u32_e64 s[26:27], v28, v27
	v_cndmask_b32_e64 v124, 0, 1.0, vcc
	v_add_u32_e32 v234, s44, v29
	v_or_b32_e32 v29, 1, v25
	v_lshlrev_b32_e32 v28, 1, v25
	v_cmp_eq_u32_e32 vcc, v25, v27
	v_add_u32_e32 v243, s44, v30
	s_waitcnt lgkmcnt(0)
; __device__ void rwkv_prep_item(const Params& p, char* lds_, int item, PrepRaw& raw, int next_item) {
;     ...
;   const int t = tid >> 3, cg8 = (tid & 7) * 8;
;   const int pos = c * 64 + t;
;   const size_t tokrow = (size_t)b * SEQ + pos;
;   const u16* prow = p.PB + tokrow * PBW;
;   const bool hasprev = pos > 0;
;   float rr[8], kk_[8], vv[8];
;   f32x4 pdb[2], pib[2], pkk[2], pka[2], prk[2];
;   {
;     const int cbp = hd * 64 + cg8;
; #pragma unroll
;     for (int q = 0; q < 2; ++q) {
;       pdb[q] = *(const f32x4*)(p.decay_bias + cbp + 4 * q); pib[q] = *(const f32x4*)(p.iclr_bias + cbp + 4 * q);
;       pkk[q] = *(const f32x4*)(p.k_k + cbp + 4 * q); pka[q] = *(const f32x4*)(p.k_a + cbp + 4 * q); prk[q] = *(const f32x4*)(p.r_k + cbp + 4 * q);
;     }
;   }
;     ...
;     *(u32x4*)(DUs + t * LD + cg8) = *(const u32x4*)(p.DUt + (size_t)(hd * 64 + t) * 64 + cg8);
;     *(u32x4*)(IUs + t * LD + cg8) = *(const u32x4*)(p.IUt + (size_t)(hd * 64 + t) * 64 + cg8);
	v_lshl_add_u64 v[130:131], s[60:61], 0, v[118:119]
	v_or_b32_e32 v118, 0x1900, v40
	s_load_dwordx4 s[44:47], s[0:1], 0x128
	v_add_u32_e32 v38, s4, v32
	v_add_u32_e32 v187, v23, v31
	v_lshl_add_u32 v221, v115, 3, v23
	v_add_u32_e32 v233, v23, v26
	v_add_u32_e32 v239, v23, v28
	v_cndmask_b32_e64 v126, 0, 1.0, vcc
	v_cmp_eq_u32_e32 vcc, v29, v27
	v_or_b32_e32 v23, 3, v25
	v_lshl_add_u64 v[132:133], s[60:61], 0, v[118:119]
	v_lshlrev_b32_e32 v118, 7, v240
	v_add_u32_e32 v162, v33, v31
	v_add_u32_e32 v34, s10, v31
	v_add_u32_e32 v166, v38, v31
	v_add_u32_e32 v188, v43, v31
	v_add_u32_e32 v235, v44, v30
	v_cndmask_b32_e64 v127, 0, 1.0, vcc
	v_cmp_lt_u32_e64 s[40:41], v23, v27
	v_cmp_gt_u32_e64 s[42:43], v23, v27
	v_cmp_eq_u32_e32 vcc, v23, v27
	v_mov_b32_e32 v23, v119
	v_lshl_add_u64 v[30:31], s[84:85], 0, v[118:119]
	v_lshlrev_b32_e32 v118, 7, v27
	v_cmp_lt_u32_e64 s[28:29], v25, v27
	v_cmp_gt_u32_e64 s[30:31], v25, v27
	v_or_b32_e32 v25, 2, v25
	v_lshl_add_u64 v[134:135], s[52:53], 0, v[22:23]
	v_lshl_add_u64 v[136:137], s[54:55], 0, v[22:23]
	v_lshl_add_u64 v[138:139], v[30:31], 0, v[22:23]
	v_lshl_add_u64 v[22:23], s[56:57], 0, v[118:119]
	v_mov_b32_e32 v121, v119
	v_cmp_lt_u32_e64 s[36:37], v25, v27
	v_cmp_gt_u32_e64 s[38:39], v25, v27
	v_cndmask_b32_e64 v129, 0, 1.0, vcc
	v_cmp_eq_u32_e32 vcc, v25, v27
	v_lshl_add_u64 v[22:23], v[22:23], 0, v[120:121]
	v_mov_b32_e32 v25, v119
	v_cmp_lt_u32_e64 s[34:35], v29, v27
	v_lshl_add_u64 v[140:141], v[22:23], 0, v[24:25]
	s_waitcnt lgkmcnt(0)
	v_lshl_add_u64 v[22:23], s[44:45], 0, v[118:119]
	v_mov_b32_e32 v27, v119
	v_mov_b32_e32 v29, v119
	v_add_u32_e32 v163, v34, v35
	v_add3_u32 v164, s10, v35, v37
	v_add3_u32 v165, s10, v37, v35
	v_add3_u32 v169, s5, v37, v35
	v_mul_u32_u24_e32 v42, 0x880, v158
	v_add_u32_e32 v45, s10, v32
	s_movk_i32 s10, 0x80
	v_mul_u32_u24_e32 v51, 0x44, v115
	s_movk_i32 s12, 0x100
	v_mul_u32_u24_e32 v53, 0x84, v115
	v_lshlrev_b32_e32 v35, 5, v46
	v_lshl_add_u64 v[142:143], v[22:23], 0, v[26:27]
	v_lshl_add_u64 v[24:25], s[58:59], 0, v[118:119]
	v_lshl_add_u64 v[30:31], s[46:47], 0, v[118:119]
	v_lshl_add_u64 v[148:149], v[22:23], 0, v[28:29]
	v_add_u32_e32 v22, -1, v158
	v_bfe_u32 v121, v223, 6, 3
	s_mov_b32 s75, 0
	v_lshl_add_u32 v182, v223, 2, s74
	v_cmp_gt_u32_e64 s[4:5], 64, v223
	v_cmp_lt_u32_e64 s[6:7], 63, v223
	v_cmp_eq_u32_e64 s[8:9], 63, v240
	v_add_u32_e32 v186, 0xfd00, v185
	v_cmp_gt_u32_e64 s[10:11], s10, v223
	v_mul_u32_u24_e32 v209, 0x110, v115
	v_cmp_gt_u32_e64 s[12:13], s12, v223
	v_add_u32_e32 v210, v44, v114
	v_add_u32_e32 v227, v34, v32
	v_add_u32_e32 v230, v33, v26
	v_add_u32_e32 v231, v38, v26
	v_add_u32_e32 v232, v45, v26
	v_add_u32_e32 v236, v33, v28
	v_add_u32_e32 v237, v38, v28
	v_add_u32_e32 v238, v45, v28
	v_cndmask_b32_e64 v128, 0, 1.0, vcc
	v_lshl_add_u64 v[144:145], v[24:25], 0, v[26:27]
	v_lshl_add_u64 v[146:147], v[30:31], 0, v[26:27]
	v_lshl_add_u64 v[150:151], v[24:25], 0, v[28:29]
	v_lshl_add_u64 v[152:153], v[30:31], 0, v[28:29]
	v_cmp_lt_u32_e64 s[44:45], 6, v22
	v_and_b32_e32 v244, 8, v158
	v_cmp_ne_u32_e64 s[46:47], 0, v121
	v_add_u32_e32 v245, s74, v39
	s_movk_i32 s53, 0xd00
	s_mov_b32 s52, 0xbf1b4598
	v_add_u32_e32 v246, v49, v50
	v_add_u32_e32 v247, v208, v51
	v_add_u32_e32 v248, v49, v48
	v_add_u32_e32 v249, v47, v52
	v_add_u32_e32 v250, v47, v53
	v_add_u32_e32 v251, v221, v35
	v_add_u32_e32 v252, v41, v42
	s_mov_b32 s54, s2
	global_load_dwordx4 v[200:203], v[132:133], off
	s_and_b32 s94, s2, 0x1c0
	v_add_lshl_u32 v196, s94, v240, 7
	v_mov_b32_e32 v197, 0
	v_mov_b64_e32 v[158:159], v[196:197]
	v_lshl_add_u64 v[196:197], v[136:137], 0, v[196:197]
	global_load_dwordx4 v[196:199], v[196:197], off
	v_lshl_add_u64 v[158:159], v[134:135], 0, v[158:159]
	global_load_dwordx4 v[158:161], v[158:159], off
	s_branch .LBB0_277

; __device__ void rwkv_prep_item(const Params& p, char* lds_, int item, PrepRaw& raw, int next_item) {
;     ...
;   {
;     const int cbp = hd * 64 + cg8;
; #pragma unroll
;     for (int q = 0; q < 2; ++q) {
;       pdb[q] = *(const f32x4*)(p.decay_bias + cbp + 4 * q); pib[q] = *(const f32x4*)(p.iclr_bias + cbp + 4 * q);
;       pkk[q] = *(const f32x4*)(p.k_k + cbp + 4 * q); pka[q] = *(const f32x4*)(p.k_a + cbp + 4 * q); prk[q] = *(const f32x4*)(p.r_k + cbp + 4 * q);
;     }
;   }
;   __syncthreads();
;   {
;     auto ldshift = [&](int col, float (&o)[8], const u32x4 cur) {
;       u32x4 prv; prv.x = prv.y = prv.z = prv.w = 0u;
;       if (hasprev) prv = *(const u32x4*)(prow - PBW + col);
.LBB0_277:
	s_and_b32 s55, s54, 0x1c0
	v_or_b32_e32 v23, s55, v116
	v_lshlrev_b32_e32 v22, 2, v23
	global_load_dwordx4 v[66:69], v22, s[64:65]
	global_load_dwordx4 v[192:195], v[132:133], off offset:16
	s_lshl_b32 s57, s54, 6
	s_ashr_i32 s56, s54, 9
	s_and_b32 s57, s57, 0xfc0
	v_add_u32_e32 v118, s57, v240
	s_ashr_i32 s57, s56, 31
	s_lshl_b64 s[56:57], s[56:57], 12
	v_lshl_add_u64 v[24:25], s[56:57], 0, v[118:119]
	v_mov_b64_e32 v[26:27], s[78:79]
	v_mad_u64_u32 v[156:157], s[56:57], v24, s53, v[26:27]
	v_mad_i32_i24 v157, v25, s53, v157
	v_cmp_ne_u32_e32 vcc, 0, v118
	v_lshlrev_b32_e32 v118, 1, v23
	v_mov_b32_e32 v78, 0
	v_mov_b32_e32 v79, 0
	v_mov_b32_e32 v80, 0
	v_mov_b32_e32 v81, 0
	s_barrier
	s_and_saveexec_b64 s[56:57], vcc
	s_cbranch_execz .LBB0_279
	v_lshl_add_u64 v[24:25], v[156:157], 0, v[118:119]
	global_load_dwordx4 v[78:81], v[24:25], off offset:-3328

; __device__ __forceinline__ unsigned pk2(float lo, float hi) { f32x2_t v = {lo, hi}; bf16x2_t b = __builtin_convertvector(v, bf16x2_t); return __builtin_bit_cast(unsigned, b); }
; __device__ __forceinline__ float bflo(unsigned v) { return __uint_as_float(v << 16); }
; __device__ __forceinline__ float bfhi(unsigned v) { return __uint_as_float(v & 0xffff0000u); }
; __device__ __forceinline__ float fexp(float x) { return __builtin_amdgcn_exp2f(x * 1.44269504088896f); }
; __device__ void rwkv_prep_item(const Params& p, char* lds_, int item, PrepRaw& raw, int next_item) {
;     ...
;     auto ldshift = [&](int col, float (&o)[8], const u32x4 cur) {
;       u32x4 prv; prv.x = prv.y = prv.z = prv.w = 0u;
;       if (hasprev) prv = *(const u32x4*)(prow - PBW + col);
;       const f32x4 m0 = *(const f32x4*)(p.shift_mu + col), m1 = *(const f32x4*)(p.shift_mu + col + 4);
;       const unsigned cw[4] = {cur.x, cur.y, cur.z, cur.w}, pw[4] = {prv.x, prv.y, prv.z, prv.w};
; #pragma unroll
;       for (int q = 0; q < 4; ++q) {
;         const float c0 = bflo(cw[q]), c1 = bfhi(cw[q]), p0 = bflo(pw[q]), p1 = bfhi(pw[q]);
;         const float mu0 = (q < 2) ? m0[2 * q] : m1[2 * q - 4], mu1 = (q < 2) ? m0[2 * q + 1] : m1[2 * q - 3];
;         o[2 * q] = c0 + (p0 - c0) * mu0;
;         o[2 * q + 1] = c1 + (p1 - c1) * mu1;
;       }
;     };
;     ldshift(hd * 64 + cg8, rr, raw.cur[0]);
;     ldshift(512 + hd * 64 + cg8, kk_, raw.cur[1]);
;     ldshift(1024 + hd * 64 + cg8, vv, raw.cur[2]);
;     float wd[8], ad[8];
;     ldshift(1536 + cg8, wd, raw.cur[3]);
;     ldshift(1600 + cg8, ad, raw.cur[4]);
;     u32x4 w;
;     float th[8];
; #pragma unroll
;     for (int e = 0; e < 8; ++e) th[e] = 1.f - 2.f * __builtin_amdgcn_rcpf(1.f + fexp(2.f * wd[e]));
;     w.x = pk2(th[0], th[1]); w.y = pk2(th[2], th[3]); w.z = pk2(th[4], th[5]); w.w = pk2(th[6], th[7]);
.LBB0_291:
	s_or_b64 exec, exec, s[56:57]
	s_waitcnt vmcnt(19)
	v_lshlrev_b32_e32 v118, 16, v10
	v_and_b32_e32 v155, 0xffff0000, v10
	s_waitcnt vmcnt(2)
	v_lshlrev_b32_e32 v156, 16, v102
	v_and_b32_e32 v102, 0xffff0000, v102
	v_sub_f32_e32 v156, v156, v118
	v_sub_f32_e32 v102, v102, v155
	s_waitcnt vmcnt(0)
	v_fmac_f32_e32 v118, v110, v156
	v_fmac_f32_e32 v155, v111, v102
	v_lshlrev_b32_e32 v110, 16, v11
	v_lshlrev_b32_e32 v102, 16, v103
	v_and_b32_e32 v111, 0xffff0000, v11
	v_and_b32_e32 v103, 0xffff0000, v103
	v_sub_f32_e32 v102, v102, v110
	v_fmac_f32_e32 v110, v112, v102
	v_sub_f32_e32 v102, v103, v111
	v_fmac_f32_e32 v111, v113, v102
	v_lshlrev_b32_e32 v112, 16, v12
	v_lshlrev_b32_e32 v102, 16, v104
	v_and_b32_e32 v113, 0xffff0000, v12
	v_and_b32_e32 v103, 0xffff0000, v104
	v_sub_f32_e32 v102, v102, v112
	v_fmac_f32_e32 v112, v106, v102
	v_sub_f32_e32 v102, v103, v113
	v_fmac_f32_e32 v113, v107, v102
	v_and_b32_e32 v102, 0xffff0000, v105
	v_and_b32_e32 v156, 0xffff0000, v13
	v_sub_f32_e32 v102, v102, v156
	v_lshlrev_b32_e32 v103, 16, v105
	v_lshlrev_b32_e32 v157, 16, v13
	v_fmac_f32_e32 v156, v109, v102
	v_and_b32_e32 v104, 0xffff0000, v2
	v_lshlrev_b32_e32 v102, 16, v90
	v_and_b32_e32 v90, 0xffff0000, v90
	v_sub_f32_e32 v103, v103, v157
	v_lshlrev_b32_e32 v105, 16, v2
	v_sub_f32_e32 v90, v90, v104
	v_fmac_f32_e32 v157, v108, v103
	v_sub_f32_e32 v102, v102, v105
	v_fmac_f32_e32 v104, v99, v90
	v_lshlrev_b32_e32 v103, 16, v3
	v_lshlrev_b32_e32 v90, 16, v91
	v_fmac_f32_e32 v105, v98, v102
	v_and_b32_e32 v102, 0xffff0000, v3
	v_and_b32_e32 v91, 0xffff0000, v91
	v_sub_f32_e32 v90, v90, v103
	v_fmac_f32_e32 v103, v100, v90
	v_sub_f32_e32 v90, v91, v102
	v_fmac_f32_e32 v102, v101, v90
	v_lshlrev_b32_e32 v99, 16, v4
	v_lshlrev_b32_e32 v90, 16, v92
	v_and_b32_e32 v98, 0xffff0000, v4
	v_and_b32_e32 v91, 0xffff0000, v92
	v_sub_f32_e32 v90, v90, v99
	v_fmac_f32_e32 v99, v94, v90
	v_sub_f32_e32 v90, v91, v98
	v_fmac_f32_e32 v98, v95, v90
	v_and_b32_e32 v90, 0xffff0000, v93
	v_and_b32_e32 v92, 0xffff0000, v5
	v_lshlrev_b32_e32 v91, 16, v93
	v_lshlrev_b32_e32 v93, 16, v5
	v_sub_f32_e32 v90, v90, v92
	v_sub_f32_e32 v91, v91, v93
	v_fmac_f32_e32 v92, v97, v90
	v_and_b32_e32 v90, 0xffff0000, v6
	v_lshlrev_b32_e32 v94, 16, v78
	v_and_b32_e32 v78, 0xffff0000, v78
	v_fmac_f32_e32 v93, v96, v91
	v_lshlrev_b32_e32 v91, 16, v6
	v_sub_f32_e32 v78, v78, v90
	v_sub_f32_e32 v94, v94, v91
	v_fmac_f32_e32 v90, v87, v78
	v_lshlrev_b32_e32 v87, 16, v7
	v_lshlrev_b32_e32 v78, 16, v79
	v_fmac_f32_e32 v91, v86, v94
	v_and_b32_e32 v86, 0xffff0000, v7
	v_and_b32_e32 v79, 0xffff0000, v79
	v_sub_f32_e32 v78, v78, v87
	v_fmac_f32_e32 v87, v88, v78
	v_sub_f32_e32 v78, v79, v86
	v_fmac_f32_e32 v86, v89, v78
	v_lshlrev_b32_e32 v89, 16, v8
	v_lshlrev_b32_e32 v78, 16, v80
	v_and_b32_e32 v88, 0xffff0000, v8
	v_and_b32_e32 v79, 0xffff0000, v80
	v_sub_f32_e32 v78, v78, v89
	v_fmac_f32_e32 v89, v78, v82
	v_sub_f32_e32 v78, v79, v88
	v_fmac_f32_e32 v88, v78, v83
	v_and_b32_e32 v78, 0xffff0000, v81
	v_lshlrev_b32_e32 v79, 16, v81
	v_and_b32_e32 v82, 0xffff0000, v9
	v_lshlrev_b32_e32 v83, 16, v9
	v_sub_f32_e32 v79, v79, v83
	v_sub_f32_e32 v78, v78, v82
	v_fmac_f32_e32 v83, v79, v84
	v_fmac_f32_e32 v82, v78, v85
	v_add_f32_e32 v84, v118, v118
	v_add_f32_e32 v85, v155, v155
	v_add_f32_e32 v100, v110, v110
	v_add_f32_e32 v101, v111, v111
	v_add_f32_e32 v106, v112, v112
	v_add_f32_e32 v107, v113, v113
	v_add_f32_e32 v108, v157, v157
	v_add_f32_e32 v109, v156, v156
	v_mul_f32_e32 v84, 0x3fb8aa3b, v84
	v_mul_f32_e32 v85, 0x3fb8aa3b, v85
	v_mul_f32_e32 v100, 0x3fb8aa3b, v100
	v_mul_f32_e32 v101, 0x3fb8aa3b, v101
	v_mul_f32_e32 v106, 0x3fb8aa3b, v106
	v_mul_f32_e32 v107, 0x3fb8aa3b, v107
	v_mul_f32_e32 v108, 0x3fb8aa3b, v108
	v_mul_f32_e32 v109, 0x3fb8aa3b, v109
	v_exp_f32_e32 v84, v84
	v_exp_f32_e32 v85, v85
	v_exp_f32_e32 v100, v100
	v_exp_f32_e32 v101, v101
	v_exp_f32_e32 v106, v106
	v_exp_f32_e32 v107, v107
	v_exp_f32_e32 v108, v108
	v_exp_f32_e32 v109, v109
	v_lshlrev_b32_e32 v110, 16, v14
	v_and_b32_e32 v111, 0xffff0000, v14
	v_lshlrev_b32_e32 v112, 16, v74
	v_and_b32_e32 v113, 0xffff0000, v74
	v_pk_add_f32 v[112:113], v[112:113], v[110:111] neg_lo:[0,1] neg_hi:[0,1]
	v_add_f32_e32 v84, 1.0, v84
	v_add_f32_e32 v85, 1.0, v85
	v_add_f32_e32 v100, 1.0, v100
	v_add_f32_e32 v101, 1.0, v101
	v_add_f32_e32 v106, 1.0, v106
	v_add_f32_e32 v107, 1.0, v107
	v_add_f32_e32 v108, 1.0, v108
	v_add_f32_e32 v109, 1.0, v109
	v_lshlrev_b32_e32 v74, 16, v75
	v_and_b32_e32 v75, 0xffff0000, v75
	v_rcp_f32_e32 v84, v84
	v_rcp_f32_e32 v85, v85
	v_rcp_f32_e32 v100, v100
	v_rcp_f32_e32 v101, v101
	v_rcp_f32_e32 v106, v106
	v_rcp_f32_e32 v107, v107
	v_rcp_f32_e32 v108, v108
	v_rcp_f32_e32 v109, v109
	v_pk_fma_f32 v[84:85], v[84:85], 2.0, 1.0 op_sel_hi:[1,0,0] neg_lo:[1,0,0] neg_hi:[1,0,0]
	v_pk_fma_f32 v[100:101], v[100:101], 2.0, 1.0 op_sel_hi:[1,0,0] neg_lo:[1,0,0] neg_hi:[1,0,0]
	v_pk_fma_f32 v[106:107], v[106:107], 2.0, 1.0 op_sel_hi:[1,0,0] neg_lo:[1,0,0] neg_hi:[1,0,0]
	v_pk_fma_f32 v[108:109], v[108:109], 2.0, 1.0 op_sel_hi:[1,0,0] neg_lo:[1,0,0] neg_hi:[1,0,0]
	v_add_lshl_u32 v118, s55, v240, 7
	v_mul_f32_e32 v67, v67, v104
	v_mul_f32_e32 v66, v66, v105
	v_mul_f32_e32 v68, v68, v103
	v_mul_f32_e32 v69, v69, v102
	s_add_i32 s90, s54, s50
	s_waitcnt vmcnt(0)
; __device__ __forceinline__ unsigned pk2(float lo, float hi) { f32x2_t v = {lo, hi}; bf16x2_t b = __builtin_convertvector(v, bf16x2_t); return __builtin_bit_cast(unsigned, b); }
; __device__ void rwkv_prep_item(const Params& p, char* lds_, int item, PrepRaw& raw, int next_item) {
;     ...
;     w.x = pk2(th[0], th[1]); w.y = pk2(th[2], th[3]); w.z = pk2(th[4], th[5]); w.w = pk2(th[6], th[7]);
;     *(u32x4*)(TW + t * LD + cg8) = w;
;     w.x = pk2(ad[0], ad[1]); w.y = pk2(ad[2], ad[3]); w.z = pk2(ad[4], ad[5]); w.w = pk2(ad[6], ad[7]);
;     *(u32x4*)(AD + t * LD + cg8) = w;
;     *(u32x4*)(DUs + t * LD + cg8) = *(const u32x4*)(p.DUt + (size_t)(hd * 64 + t) * 64 + cg8);
;     *(u32x4*)(IUs + t * LD + cg8) = *(const u32x4*)(p.IUt + (size_t)(hd * 64 + t) * 64 + cg8);
;   }
;   __syncthreads();
;   const int it = wave >> 1, jt0 = (wave & 1) * 2, mr = lane & 15, mg = lane >> 4;
;   const int mi = it * 16 + mr;
;   {
;     f32x4 a1[2], a2[2]; zero2(a1); zero2(a2);
;     mm_nt(TW, DUs, a1, wave, lane);
;     mm_nt(AD, IUs, a2, wave, lane);
; #pragma unroll
;     for (int jj = 0; jj < 2; ++jj) {
;       *(f32x4*)(Zw + mi * 68 + (jt0 + jj) * 16 + 4 * mg) = a1[jj];
;       *(f32x4*)(Za + mi * 68 + (jt0 + jj) * 16 + 4 * mg) = a2[jj];
;     }
;   }
;   __syncthreads();
	v_pk_fma_f32 v[94:95], v[200:201], v[112:113], v[110:111]
	v_lshlrev_b32_e32 v110, 16, v15
	v_and_b32_e32 v111, 0xffff0000, v15
	v_pk_add_f32 v[74:75], v[74:75], v[110:111] neg_lo:[0,1] neg_hi:[0,1]
	s_nop 0
	v_pk_fma_f32 v[96:97], v[202:203], v[74:75], v[110:111]
	v_lshlrev_b32_e32 v74, 16, v16
	v_and_b32_e32 v75, 0xffff0000, v16
	v_lshlrev_b32_e32 v110, 16, v76
	v_and_b32_e32 v111, 0xffff0000, v76
	v_pk_add_f32 v[110:111], v[110:111], v[74:75] neg_lo:[0,1] neg_hi:[0,1]
	v_lshlrev_b32_e32 v76, 16, v17
	v_pk_fma_f32 v[78:79], v[192:193], v[110:111], v[74:75]
	v_lshlrev_b32_e32 v74, 16, v77
	v_and_b32_e32 v75, 0xffff0000, v77
	v_and_b32_e32 v77, 0xffff0000, v17
	v_pk_add_f32 v[74:75], v[74:75], v[76:77] neg_lo:[0,1] neg_hi:[0,1]
	s_nop 0
	v_pk_fma_f32 v[80:81], v[194:195], v[74:75], v[76:77]
	v_cvt_pk_bf16_f32 v74, v84, v85
	v_cvt_pk_bf16_f32 v75, v100, v101
	v_cvt_pk_bf16_f32 v76, v106, v107
	v_cvt_pk_bf16_f32 v77, v108, v109
	ds_write_b128 v117, v[74:77]
	v_cvt_pk_bf16_f32 v74, v94, v95
	v_cvt_pk_bf16_f32 v75, v96, v97
	v_cvt_pk_bf16_f32 v76, v78, v79
	v_cvt_pk_bf16_f32 v77, v80, v81
	ds_write_b128 v117, v[74:77] offset:9216
	v_mul_f32_e32 v85, v67, v67
	v_fmac_f32_e32 v85, v66, v66
	v_fmac_f32_e32 v85, v68, v68
	v_fmac_f32_e32 v85, v69, v69
	ds_write_b128 v117, v[158:161] offset:18432
	ds_write_b128 v117, v[196:199] offset:27648
	s_and_b32 s94, s90, 0x1c0
	v_add_lshl_u32 v196, s94, v240, 7
	v_mov_b32_e32 v197, 0
	v_mov_b64_e32 v[158:159], v[196:197]
	v_lshl_add_u64 v[196:197], v[136:137], 0, v[196:197]
	global_load_dwordx4 v[196:199], v[196:197], off
	v_lshl_add_u64 v[158:159], v[134:135], 0, v[158:159]
	global_load_dwordx4 v[158:161], v[158:159], off
	v_or_b32_e32 v58, s55, v116
	v_lshlrev_b32_e32 v58, 2, v58
	global_load_dwordx4 v[34:37], v58, s[62:63] offset:16
	global_load_dwordx4 v[38:41], v58, s[62:63]
	global_load_dwordx4 v[54:57], v58, s[80:81] offset:16
	global_load_dwordx4 v[70:73], v58, s[80:81]
	global_load_dwordx4 v[46:49], v58, s[64:65] offset:16
	global_load_dwordx4 v[50:53], v58, s[66:67] offset:16
	global_load_dwordx4 v[62:65], v58, s[66:67]
	global_load_dwordx4 v[42:45], v58, s[82:83] offset:16
	global_load_dwordx4 v[58:61], v58, s[82:83]
	s_waitcnt lgkmcnt(0)
	s_barrier
	ds_read_b128 v[74:77], v162
	ds_read_b128 v[78:81], v163
	ds_read_b128 v[94:97], v163 offset:2304
	s_waitcnt lgkmcnt(1)
	v_mfma_f32_16x16x32_bf16 v[78:81], v[78:81], v[74:77], 0
	s_waitcnt lgkmcnt(0)
	v_mfma_f32_16x16x32_bf16 v[74:77], v[94:97], v[74:77], 0
	ds_read_b128 v[94:97], v162 offset:64
	ds_read_b128 v[106:109], v164
	s_waitcnt lgkmcnt(0)
	v_mfma_f32_16x16x32_bf16 v[78:81], v[106:109], v[94:97], v[78:81]
	ds_read_b128 v[106:109], v165 offset:2304
	s_waitcnt lgkmcnt(0)
	v_mfma_f32_16x16x32_bf16 v[74:77], v[106:109], v[94:97], v[74:77]
	ds_read_b128 v[94:97], v166
	ds_read_b128 v[106:109], v167
	ds_read_b128 v[110:113], v167 offset:2304
	s_waitcnt lgkmcnt(1)
	v_mfma_f32_16x16x32_bf16 v[106:109], v[106:109], v[94:97], 0
	s_waitcnt lgkmcnt(0)
	v_mfma_f32_16x16x32_bf16 v[94:97], v[110:113], v[94:97], 0
	ds_read_b128 v[110:113], v166 offset:64
	ds_read_b128 v[192:195], v168
	s_waitcnt lgkmcnt(0)
	v_mfma_f32_16x16x32_bf16 v[106:109], v[192:195], v[110:113], v[106:109]
	ds_read_b128 v[192:195], v169 offset:2304
	s_waitcnt lgkmcnt(0)
	v_mfma_f32_16x16x32_bf16 v[94:97], v[192:195], v[110:113], v[94:97]
	ds_write_b128 v170, v[78:81]
	s_nop 3
	ds_write_b128 v171, v[106:109]
	ds_write_b128 v170, v[74:77] offset:64
	s_nop 0
	ds_write_b128 v171, v[94:97] offset:64
	s_waitcnt lgkmcnt(0)
	s_barrier
; __device__ __forceinline__ float fsigmoid(float x) { return __builtin_amdgcn_rcpf(1.f + fexp(-x)); }
; __device__ void rwkv_prep_item(const Params& p, char* lds_, int item, PrepRaw& raw, int next_item) {
;     ...
;   float av[8], bv[8], k2[8], lw[8];
;   float bon;
;   {
;     float ss = 0.f; bon = 0.f;
;     float kk[8], ai[8];
; #pragma unroll
;     for (int e = 0; e < 8; ++e) {
;       const float zw = Zw[t * 68 + cg8 + e] + pdb[e >> 2][e & 3];
;       const float za = Za[t * 68 + cg8 + e] + pib[e >> 2][e & 3];
;       lw[e] = -0.6065306597126334f * fsigmoid(zw);
;       ai[e] = fsigmoid(za);
;       kk[e] = kk_[e] * pkk[e >> 2][e & 3];
;       k2[e] = kk_[e] * (1.f + (ai[e] - 1.f) * pka[e >> 2][e & 3]);
;       ss += kk[e] * kk[e];
;       bon += rr[e] * k2[e] * prk[e >> 2][e & 3];
;     }
;     ss += __shfl_xor(ss, 1); ss += __shfl_xor(ss, 2); ss += __shfl_xor(ss, 4);
;     bon += __shfl_xor(bon, 1); bon += __shfl_xor(bon, 2); bon += __shfl_xor(bon, 4);
;     const float inv = __builtin_amdgcn_rsqf(fmaxf(ss, 1e-24f));
; #pragma unroll
;     for (int e = 0; e < 8; ++e) { const float kn = kk[e] * inv; av[e] = -kn; bv[e] = kn * ai[e]; }
;   }
;   __builtin_amdgcn_sched_barrier(0);
;   if (next_item < 4096) prep_load(p, next_item, raw);
	ds_read_b128 v[74:77], v172
	ds_read_b128 v[78:81], v173
	s_waitcnt vmcnt(0) lgkmcnt(0)
	v_add_f32_e32 v70, v70, v78
	v_mul_f32_e32 v70, 0xbfb8aa3b, v70
	v_exp_f32_e32 v70, v70
	s_nop 0
	v_add_f32_e32 v70, 1.0, v70
	v_rcp_f32_e32 v70, v70
	s_nop 0
	v_add_f32_e32 v78, -1.0, v70
	v_fma_f32 v62, v62, v78, 1.0
	v_mul_f32_e32 v62, v105, v62
	v_mul_f32_e32 v78, v91, v62
	v_fma_f32 v84, v58, v78, 0
	v_add_f32_e32 v58, v71, v79
	v_mul_f32_e32 v58, 0xbfb8aa3b, v58
	v_exp_f32_e32 v58, v58
	s_nop 0
	v_add_f32_e32 v58, 1.0, v58
	v_rcp_f32_e32 v71, v58
	s_nop 0
	v_add_f32_e32 v58, -1.0, v71
	v_fma_f32 v58, v63, v58, 1.0
	v_mul_f32_e32 v63, v104, v58
	v_mul_f32_e32 v58, v90, v63
	v_fmac_f32_e32 v84, v59, v58
	v_add_f32_e32 v58, v72, v80
	v_mul_f32_e32 v58, 0xbfb8aa3b, v58
	v_exp_f32_e32 v58, v58
	s_nop 0
	v_add_f32_e32 v58, 1.0, v58
	v_rcp_f32_e32 v72, v58
	s_nop 0
	v_add_f32_e32 v58, -1.0, v72
	v_fma_f32 v58, v64, v58, 1.0
	v_mul_f32_e32 v64, v103, v58
	v_mul_f32_e32 v58, v87, v64
	v_fmac_f32_e32 v84, v60, v58
	v_add_f32_e32 v58, v73, v81
	v_mul_f32_e32 v58, 0xbfb8aa3b, v58
	v_exp_f32_e32 v58, v58
	s_nop 0
	v_add_f32_e32 v58, 1.0, v58
	v_rcp_f32_e32 v73, v58
	s_nop 0
	v_add_f32_e32 v58, -1.0, v73
	v_fma_f32 v58, v65, v58, 1.0
	v_mul_f32_e32 v65, v102, v58
	v_mul_f32_e32 v58, v86, v65
	v_fmac_f32_e32 v84, v61, v58
	ds_read_b128 v[58:61], v176
	ds_read_b128 v[78:81], v177
	s_waitcnt lgkmcnt(0)
	v_add_f32_e32 v54, v54, v78
	v_mul_f32_e32 v54, 0xbfb8aa3b, v54
	v_exp_f32_e32 v54, v54
	v_mul_f32_e32 v78, v46, v99
	v_fmac_f32_e32 v85, v78, v78
	v_add_f32_e32 v54, 1.0, v54
	v_rcp_f32_e32 v54, v54
	s_nop 0
	v_add_f32_e32 v46, -1.0, v54
	v_fma_f32 v46, v50, v46, 1.0
	v_mul_f32_e32 v46, v99, v46
	v_mul_f32_e32 v50, v89, v46
	v_fmac_f32_e32 v84, v42, v50
	v_add_f32_e32 v42, v55, v79
	v_mul_f32_e32 v42, 0xbfb8aa3b, v42
	v_exp_f32_e32 v42, v42
	v_mul_f32_e32 v55, v47, v98
	v_fmac_f32_e32 v85, v55, v55
	v_mul_f32_e32 v79, v49, v92
	v_add_f32_e32 v42, 1.0, v42
	v_rcp_f32_e32 v50, v42
	s_nop 0
	v_add_f32_e32 v42, -1.0, v50
	v_fma_f32 v42, v51, v42, 1.0
	v_mul_f32_e32 v47, v98, v42
	v_mul_f32_e32 v42, v88, v47
	v_fmac_f32_e32 v84, v43, v42
	v_add_f32_e32 v42, v56, v80
	v_mul_f32_e32 v42, 0xbfb8aa3b, v42
	v_exp_f32_e32 v42, v42
	v_mul_f32_e32 v56, v48, v93
	v_fmac_f32_e32 v85, v56, v56
	v_fmac_f32_e32 v85, v79, v79
	v_add_f32_e32 v42, 1.0, v42
	v_rcp_f32_e32 v51, v42
	s_nop 0
	v_add_f32_e32 v42, -1.0, v51
	v_fma_f32 v42, v52, v42, 1.0
	v_mul_f32_e32 v52, v93, v42
	v_mul_f32_e32 v42, v83, v52
	v_fmac_f32_e32 v84, v44, v42
	v_add_f32_e32 v42, v57, v81
	v_mul_f32_e32 v42, 0xbfb8aa3b, v42
	v_exp_f32_e32 v42, v42
	s_nop 0
	v_add_f32_e32 v42, 1.0, v42
	v_rcp_f32_e32 v57, v42
	s_nop 0
	v_add_f32_e32 v42, -1.0, v57
	v_fma_f32 v42, v53, v42, 1.0
	v_mul_f32_e32 v53, v92, v42
	v_mul_f32_e32 v42, v82, v53
	v_fmac_f32_e32 v84, v45, v42
	ds_bpermute_b32 v42, v178, v85
	s_waitcnt lgkmcnt(0)
	v_add_f32_e32 v42, v85, v42
	ds_bpermute_b32 v43, v179, v42
	s_waitcnt lgkmcnt(0)
	v_add_f32_e32 v80, v42, v43
	ds_bpermute_b32 v42, v178, v84
	ds_bpermute_b32 v81, v180, v80
	s_waitcnt lgkmcnt(1)
	v_add_f32_e32 v42, v84, v42
	ds_bpermute_b32 v43, v179, v42
	s_waitcnt lgkmcnt(0)
	v_add_f32_e32 v48, v42, v43
	ds_bpermute_b32 v49, v180, v48
	s_cmpk_gt_i32 s90, 0xfff
	s_cselect_b64 s[56:57], -1, 0
	v_mov_b64_e32 v[44:45], v[20:21]
	s_and_b64 vcc, exec, s[56:57]
	v_mov_b64_e32 v[42:43], v[18:19]
	s_cbranch_vccnz .LBB0_293
	s_ashr_i32 s58, s90, 9
	s_lshl_b32 s74, s90, 6
	s_ashr_i32 s59, s58, 31
	s_and_b32 s74, s74, 0xfc0
	s_lshl_b64 s[58:59], s[58:59], 12
	v_add_u32_e32 v118, s74, v240
	v_lshl_add_u64 v[2:3], s[58:59], 0, v[118:119]
	v_mov_b64_e32 v[4:5], s[78:79]
	s_and_b32 s55, s90, 0x1c0
	v_mad_u64_u32 v[10:11], s[58:59], v2, s53, v[4:5]
	v_mad_i32_i24 v11, v3, s53, v11
	s_lshl_b32 s74, s55, 1
	v_lshl_add_u64 v[2:3], v[10:11], 0, s[74:75]
	v_mov_b32_e32 v155, v119
	v_lshl_add_u64 v[12:13], v[2:3], 0, v[154:155]
	v_lshl_add_u64 v[14:15], v[10:11], 0, v[154:155]
	global_load_dwordx4 v[6:9], v[12:13], off
	global_load_dwordx4 v[2:5], v[12:13], off offset:1024
	global_load_dwordx4 v[42:45], v[12:13], off offset:2048
	s_nop 0
	global_load_dwordx4 v[10:13], v[14:15], off offset:3072
	s_nop 0
	global_load_dwordx4 v[14:17], v[14:15], off offset:3200

; #define LAS __attribute__((address_space(3)))
; __global__ void __launch_bounds__(NT) fwd_mega(Params p) {
;   cg::grid_group grid = cg::this_grid();
;   const int bid = blockIdx.x, nb = gridDim.x;
;   volatile LAS unsigned* xst = (volatile LAS unsigned*)(dyn_lds + LDS_BYTES - 32);
	.amdhsa_kernel _Z8fwd_mega6Params
		.amdhsa_group_segment_fixed_size 0
		.amdhsa_private_segment_fixed_size 0
		.amdhsa_kernarg_size 592
		.amdhsa_user_sgpr_count 2
		.amdhsa_user_sgpr_dispatch_ptr 0
		.amdhsa_user_sgpr_queue_ptr 0
		.amdhsa_user_sgpr_kernarg_segment_ptr 1
		.amdhsa_user_sgpr_dispatch_id 0
		.amdhsa_user_sgpr_kernarg_preload_length 0
		.amdhsa_user_sgpr_kernarg_preload_offset 0
		.amdhsa_user_sgpr_private_segment_size 0
		.amdhsa_uses_dynamic_stack 0
		.amdhsa_enable_private_segment 0
		.amdhsa_system_sgpr_workgroup_id_x 1
		.amdhsa_system_sgpr_workgroup_id_y 0
		.amdhsa_system_sgpr_workgroup_id_z 0
		.amdhsa_system_sgpr_workgroup_info 0
		.amdhsa_system_vgpr_workitem_id 2
		.amdhsa_next_free_vgpr 256
		.amdhsa_next_free_sgpr 95
		.amdhsa_accum_offset 256
		.amdhsa_reserve_vcc 1
		.amdhsa_float_round_mode_32 0
		.amdhsa_float_round_mode_16_64 0
		.amdhsa_float_denorm_mode_32 3
		.amdhsa_float_denorm_mode_16_64 3
		.amdhsa_dx10_clamp 1
		.amdhsa_ieee_mode 1
		.amdhsa_fp16_overflow 0
		.amdhsa_tg_split 0
		.amdhsa_exception_fp_ieee_invalid_op 0
		.amdhsa_exception_fp_denorm_src 0
		.amdhsa_exception_fp_ieee_div_zero 0
		.amdhsa_exception_fp_ieee_overflow 0
		.amdhsa_exception_fp_ieee_underflow 0
		.amdhsa_exception_fp_ieee_inexact 0
		.amdhsa_exception_int_div_zero 0
	.end_amdhsa_kernel

; #define LAS __attribute__((address_space(3)))
; __global__ void __launch_bounds__(NT) fwd_mega(Params p) {
;   cg::grid_group grid = cg::this_grid();
;   const int bid = blockIdx.x, nb = gridDim.x;
;   volatile LAS unsigned* xst = (volatile LAS unsigned*)(dyn_lds + LDS_BYTES - 32);
amdhsa.kernels:
  - .agpr_count:     0
    .args:
      - .offset:         0
        .size:           336
        .value_kind:     by_value
      - .offset:         336
        .size:           4
        .value_kind:     hidden_block_count_x
      - .offset:         340
        .size:           4
        .value_kind:     hidden_block_count_y
      - .offset:         344
        .size:           4
        .value_kind:     hidden_block_count_z
      - .offset:         348
        .size:           2
        .value_kind:     hidden_group_size_x
      - .offset:         350
        .size:           2
        .value_kind:     hidden_group_size_y
      - .offset:         352
        .size:           2
        .value_kind:     hidden_group_size_z
      - .offset:         354
        .size:           2
        .value_kind:     hidden_remainder_x
      - .offset:         356
        .size:           2
        .value_kind:     hidden_remainder_y
      - .offset:         358
        .size:           2
        .value_kind:     hidden_remainder_z
      - .offset:         376
        .size:           8
        .value_kind:     hidden_global_offset_x
      - .offset:         384
        .size:           8
        .value_kind:     hidden_global_offset_y
      - .offset:         392
        .size:           8
        .value_kind:     hidden_global_offset_z
      - .offset:         400
        .size:           2
        .value_kind:     hidden_grid_dims
      - .offset:         424
        .size:           8
        .value_kind:     hidden_multigrid_sync_arg
      - .offset:         456
        .size:           4
        .value_kind:     hidden_dynamic_lds_size
    .group_segment_fixed_size: 0
    .kernarg_segment_align: 8
    .kernarg_segment_size: 592
    .language:       OpenCL C
    .language_version:
      - 2
      - 0
    .max_flat_workgroup_size: 512
    .name:           _Z8fwd_mega6Params
    .private_segment_fixed_size: 0
    .sgpr_count:     101
    .sgpr_spill_count: 0
    .symbol:         _Z8fwd_mega6Params.kd
    .uniform_work_group_size: 1
    .uses_dynamic_stack: false
    .vgpr_count:     256
    .vgpr_spill_count: 0
    .wavefront_size: 64
